# code placement: attention loop at 0 mod 8 plus a pad after the attention unit so later code keeps its 0 mod 8 phase
# baseline (speedup 1.0000x reference)
.LBB0_886:
	s_or_b64 exec, exec, s[22:23]
	v_or_b32_e32 v5, 28, v5
	v_lshl_add_u32 v6, v5, 8, v6
	s_waitcnt lgkmcnt(0)
	ds_read_b128 v[10:13], v6
	v_lshlrev_b32_e32 v98, 11, v5
	v_lshl_add_u64 v[2:3], v[2:3], 0, v[98:99]
	s_waitcnt lgkmcnt(0)
	global_store_dwordx4 v[2:3], v[10:13], off
	v_and_b32_e32 v3, 0xffff0000, v10
	v_lshlrev_b32_e32 v2, 16, v10
	v_and_b32_e32 v10, 0xffff0000, v11
	v_mul_f32_e32 v3, v3, v3
	v_lshlrev_b32_e32 v6, 16, v11
	v_fmac_f32_e32 v3, v2, v2
	v_mul_f32_e32 v2, v10, v10
	v_lshlrev_b32_e32 v11, 16, v12
	v_and_b32_e32 v12, 0xffff0000, v12
	v_lshlrev_b32_e32 v14, 16, v13
	v_and_b32_e32 v13, 0xffff0000, v13
	v_fmac_f32_e32 v2, v6, v6
	v_add_f32_e32 v2, v3, v2
	v_mul_f32_e32 v3, v12, v12
	v_mul_f32_e32 v6, v13, v13
	v_fmac_f32_e32 v3, v11, v11
	v_fmac_f32_e32 v6, v14, v14
	v_add_f32_e32 v3, v3, v6
	v_add_f32_e32 v2, v2, v3
	s_nop 1
	v_mov_b32_dpp v3, v2 quad_perm:[1,0,3,2] row_mask:0xf bank_mask:0xf
	s_waitcnt lgkmcnt(0)
	v_add_f32_e32 v2, v2, v3
	s_nop 1
	v_mov_b32_dpp v3, v2 quad_perm:[2,3,0,1] row_mask:0xf bank_mask:0xf
	s_waitcnt lgkmcnt(0)
	v_add_f32_e32 v2, v2, v3
	s_nop 1
	v_mov_b32_dpp v3, v2 row_half_mirror row_mask:0xf bank_mask:0xf
	s_waitcnt lgkmcnt(0)
	v_add_f32_e32 v2, v2, v3
	s_nop 1
	v_mov_b32_dpp v3, v2 row_mirror row_mask:0xf bank_mask:0xf
	s_and_saveexec_b64 s[22:23], vcc
	s_cbranch_execz .LBB0_819
	s_waitcnt lgkmcnt(0)
	v_add_f32_e32 v4, v2, v3
	v_or_b32_e32 v2, v5, v160
	v_lshlrev_b32_e32 v2, 2, v2
	v_ashrrev_i32_e32 v3, 31, v2
	v_lshl_add_u64 v[2:3], v[2:3], 2, s[0:1]
	global_store_dword v[2:3], v4, off
	s_branch .LBB0_819
	s_nop 0
